# retention: o-tile stores issued after the chunk barrier
# speedup vs baseline: 1.1032x; 1.0028x over previous
; __device__ __forceinline__ unsigned pk2(float lo, float hi) { return pg8::cvt_pk_bf16(lo, hi); }
; __device__ __forceinline__ void ret_prompt_item(LAS unsigned char* lds, const bf16_t* z, bf16_t* o, float* state_out, int item, int tid) {
;     ...
; #pragma unroll
;         for (int e4 = 0; e4 < 4; ++e4) {
;             u32x2 w; w.x = pk2(ao[e4][0], ao[e4][1]); w.y = pk2(ao[e4][2], ao[e4][3]);
;             *(u32x2*)(o + (tok0 + i) * 4096 + h * 512 + et * 64 + 16 * e4 + 4 * g) = w;
;         }
;         __syncthreads();
.Lret_noq:
	v_lshlrev_b64 v[246:247], 13, v[208:209]
	v_lshl_add_u64 v[246:247], v[200:201], 0, v[246:247]
	v_cvt_pk_bf16_f32 v122, v106, v107
	v_cvt_pk_bf16_f32 v123, v108, v109
	v_cvt_pk_bf16_f32 v124, v110, v111
	v_cvt_pk_bf16_f32 v125, v112, v113
	v_cvt_pk_bf16_f32 v126, v114, v115
	v_cvt_pk_bf16_f32 v127, v116, v117
	v_cvt_pk_bf16_f32 v128, v118, v119
	v_cvt_pk_bf16_f32 v129, v120, v121
	v_mov_b32_e32 v195, v194
	s_barrier
; #define LAS __attribute__((address_space(3)))
; #define MFMA16(a, b, c) __builtin_amdgcn_mfma_f32_16x16x32_bf16((a), (b), (c), 0, 0, 0)
; __device__ __forceinline__ unsigned pk2(float lo, float hi) { return pg8::cvt_pk_bf16(lo, hi); }
; __device__ __forceinline__ void ret_prompt_item(LAS unsigned char* lds, const bf16_t* z, bf16_t* o, float* state_out, int item, int tid) {
;     ...
;         for (int e4 = 0; e4 < 4; ++e4) {
;             u32x2 w; w.x = pk2(ao[e4][0], ao[e4][1]); w.y = pk2(ao[e4][2], ao[e4][3]);
;             *(u32x2*)(o + (tok0 + i) * 4096 + h * 512 + et * 64 + 16 * e4 + 4 * g) = w;
;         }
;         __syncthreads();
; #pragma unroll
;         for (int e4 = 0; e4 < 4; ++e4) { accS[e4][0] = accS[e4][0] * g128; accS[e4][1] = accS[e4][1] * g128; }
; #pragma unroll
;         for (int ks = 0; ks < 4; ++ks) {
;             bf16x8 kb[2];
; #pragma unroll
;             for (int dt = 0; dt < 2; ++dt) { LAS unsigned char* bp = Kn + (32 * ks + 8 * g + q4) * 528 + (16 * (2 * wave + dt) + 4 * p4) * 2; kb[dt] = tr_read8(bp, bp + 4 * 528); }
; #pragma unroll
;             for (int e4 = 0; e4 < 4; ++e4) {
;                 LAS unsigned char* ap = Vd + (32 * ks + 8 * g + q4) * 144 + (16 * e4 + 4 * p4) * 2;
;                 const bf16x8 va = tr_read8(ap, ap + 4 * 144);
;                 accS[e4][0] = MFMA16(kb[0], va, accS[e4][0]); accS[e4][1] = MFMA16(kb[1], va, accS[e4][1]);
;             }
;         }
; #pragma unroll
;         for (int e4 = 0; e4 < 4; ++e4)
; #pragma unroll
;             for (int dt = 0; dt < 2; ++dt)
;             { u32x2 w; w.x = pk2(accS[e4][dt][0], accS[e4][dt][1]); w.y = pk2(accS[e4][dt][2], accS[e4][dt][3]);
;                 *(LAS u32x2*)(St + (16 * e4 + l15) * 528 + (16 * (2 * wave + dt) + 4 * g) * 2) = w; }
;     }
	global_store_dwordx2 v[246:247], v[122:123], off
	global_store_dwordx2 v[246:247], v[124:125], off offset:32
	global_store_dwordx2 v[246:247], v[126:127], off offset:64
	global_store_dwordx2 v[246:247], v[128:129], off offset:96
	s_add_i32 s31, s31, 1
	v_pk_mul_f32 v[42:43], v[206:207], v[42:43]
	v_pk_mul_f32 v[44:45], v[194:195], v[44:45]
	v_pk_mul_f32 v[46:47], v[206:207], v[46:47]
	v_pk_mul_f32 v[48:49], v[194:195], v[48:49]
	v_pk_mul_f32 v[54:55], v[206:207], v[54:55]
	v_pk_mul_f32 v[56:57], v[194:195], v[56:57]
	v_pk_mul_f32 v[50:51], v[206:207], v[50:51]
	v_pk_mul_f32 v[52:53], v[194:195], v[52:53]
	v_pk_mul_f32 v[62:63], v[206:207], v[62:63]
	v_pk_mul_f32 v[64:65], v[194:195], v[64:65]
	v_pk_mul_f32 v[58:59], v[206:207], v[58:59]
	v_pk_mul_f32 v[60:61], v[194:195], v[60:61]
	v_pk_mul_f32 v[70:71], v[206:207], v[70:71]
	v_pk_mul_f32 v[72:73], v[194:195], v[72:73]
	v_pk_mul_f32 v[66:67], v[206:207], v[66:67]
	v_pk_mul_f32 v[68:69], v[194:195], v[68:69]
	ds_read_b64_tr_b16 v[106:107], v242
	ds_read_b64_tr_b16 v[108:109], v242 offset:2112
	ds_read_b64_tr_b16 v[110:111], v242 offset:32
	ds_read_b64_tr_b16 v[112:113], v242 offset:2144
	ds_read_b64_tr_b16 v[122:123], v243
	ds_read_b64_tr_b16 v[124:125], v243 offset:576
	ds_read_b64_tr_b16 v[126:127], v243 offset:32
	ds_read_b64_tr_b16 v[128:129], v243 offset:608
	ds_read_b64_tr_b16 v[246:247], v243 offset:64
	ds_read_b64_tr_b16 v[248:249], v243 offset:640
	ds_read_b64_tr_b16 v[250:251], v243 offset:96
	ds_read_b64_tr_b16 v[252:253], v243 offset:672
	ds_read_b64_tr_b16 v[114:115], v242 offset:16896
	ds_read_b64_tr_b16 v[116:117], v242 offset:19008
	ds_read_b64_tr_b16 v[118:119], v242 offset:16928
	ds_read_b64_tr_b16 v[120:121], v242 offset:19040
	ds_read_b64_tr_b16 v[134:135], v243 offset:4608
	ds_read_b64_tr_b16 v[136:137], v243 offset:5184
	s_waitcnt lgkmcnt(12)
	v_mfma_f32_16x16x32_bf16 v[42:45], v[106:109], v[122:125], v[42:45]
	v_mfma_f32_16x16x32_bf16 v[46:49], v[110:113], v[122:125], v[46:49]
	ds_read_b64_tr_b16 v[146:147], v243 offset:4640
	ds_read_b64_tr_b16 v[148:149], v243 offset:5216
	s_waitcnt lgkmcnt(12)
	v_mfma_f32_16x16x32_bf16 v[54:57], v[106:109], v[126:129], v[54:57]
	v_mfma_f32_16x16x32_bf16 v[50:53], v[110:113], v[126:129], v[50:53]
	ds_read_b64_tr_b16 v[150:151], v243 offset:4672
	ds_read_b64_tr_b16 v[152:153], v243 offset:5248
	s_waitcnt lgkmcnt(12)
	v_mfma_f32_16x16x32_bf16 v[62:65], v[106:109], v[246:249], v[62:65]
	v_mfma_f32_16x16x32_bf16 v[58:61], v[110:113], v[246:249], v[58:61]
	ds_read_b64_tr_b16 v[122:123], v243 offset:4704
	ds_read_b64_tr_b16 v[124:125], v243 offset:5280
	s_waitcnt lgkmcnt(12)
	v_mfma_f32_16x16x32_bf16 v[70:73], v[106:109], v[250:253], v[70:73]
	v_mfma_f32_16x16x32_bf16 v[66:69], v[110:113], v[250:253], v[66:69]
	ds_read_b64_tr_b16 v[106:107], v242 offset:33792
	ds_read_b64_tr_b16 v[108:109], v242 offset:35904
	ds_read_b64_tr_b16 v[110:111], v242 offset:33824
	ds_read_b64_tr_b16 v[112:113], v242 offset:35936
	ds_read_b64_tr_b16 v[126:127], v243 offset:9216
	ds_read_b64_tr_b16 v[128:129], v243 offset:9792
	s_waitcnt lgkmcnt(12)
	v_mfma_f32_16x16x32_bf16 v[42:45], v[114:117], v[134:137], v[42:45]
	v_mfma_f32_16x16x32_bf16 v[46:49], v[118:121], v[134:137], v[46:49]
	ds_read_b64_tr_b16 v[246:247], v243 offset:9248
	ds_read_b64_tr_b16 v[248:249], v243 offset:9824
	s_waitcnt lgkmcnt(12)
	v_mfma_f32_16x16x32_bf16 v[54:57], v[114:117], v[146:149], v[54:57]
	v_mfma_f32_16x16x32_bf16 v[50:53], v[118:121], v[146:149], v[50:53]
	ds_read_b64_tr_b16 v[250:251], v243 offset:9280
	ds_read_b64_tr_b16 v[252:253], v243 offset:9856
	s_waitcnt lgkmcnt(12)
	v_mfma_f32_16x16x32_bf16 v[62:65], v[114:117], v[150:153], v[62:65]
	v_mfma_f32_16x16x32_bf16 v[58:61], v[118:121], v[150:153], v[58:61]
	ds_read_b64_tr_b16 v[134:135], v243 offset:9312
	ds_read_b64_tr_b16 v[136:137], v243 offset:9888
	s_waitcnt lgkmcnt(12)
	v_mfma_f32_16x16x32_bf16 v[70:73], v[114:117], v[122:125], v[70:73]
	v_mfma_f32_16x16x32_bf16 v[66:69], v[118:121], v[122:125], v[66:69]
	ds_read_b64_tr_b16 v[114:115], v242 offset:50688
	ds_read_b64_tr_b16 v[116:117], v242 offset:52800
	ds_read_b64_tr_b16 v[118:119], v242 offset:50720
	ds_read_b64_tr_b16 v[120:121], v242 offset:52832
	ds_read_b64_tr_b16 v[146:147], v243 offset:13824
	ds_read_b64_tr_b16 v[148:149], v243 offset:14400
	s_waitcnt lgkmcnt(12)
	v_mfma_f32_16x16x32_bf16 v[42:45], v[106:109], v[126:129], v[42:45]
	v_mfma_f32_16x16x32_bf16 v[46:49], v[110:113], v[126:129], v[46:49]
	ds_read_b64_tr_b16 v[150:151], v243 offset:13856
	ds_read_b64_tr_b16 v[152:153], v243 offset:14432
	s_waitcnt lgkmcnt(12)
	v_mfma_f32_16x16x32_bf16 v[54:57], v[106:109], v[246:249], v[54:57]
	v_mfma_f32_16x16x32_bf16 v[50:53], v[110:113], v[246:249], v[50:53]
	ds_read_b64_tr_b16 v[122:123], v243 offset:13888
	ds_read_b64_tr_b16 v[124:125], v243 offset:14464
	s_waitcnt lgkmcnt(12)
	v_mfma_f32_16x16x32_bf16 v[62:65], v[106:109], v[250:253], v[62:65]
	v_mfma_f32_16x16x32_bf16 v[58:61], v[110:113], v[250:253], v[58:61]
	ds_read_b64_tr_b16 v[126:127], v243 offset:13920
	ds_read_b64_tr_b16 v[128:129], v243 offset:14496
	s_waitcnt lgkmcnt(12)
	v_mfma_f32_16x16x32_bf16 v[70:73], v[106:109], v[134:137], v[70:73]
	v_mfma_f32_16x16x32_bf16 v[66:69], v[110:113], v[134:137], v[66:69]
	s_waitcnt lgkmcnt(6)
	v_mfma_f32_16x16x32_bf16 v[42:45], v[114:117], v[146:149], v[42:45]
	v_mfma_f32_16x16x32_bf16 v[46:49], v[118:121], v[146:149], v[46:49]
	s_waitcnt lgkmcnt(4)
	v_mfma_f32_16x16x32_bf16 v[54:57], v[114:117], v[150:153], v[54:57]
	v_mfma_f32_16x16x32_bf16 v[50:53], v[118:121], v[150:153], v[50:53]
	s_waitcnt lgkmcnt(2)
	v_mfma_f32_16x16x32_bf16 v[62:65], v[114:117], v[122:125], v[62:65]
	v_mfma_f32_16x16x32_bf16 v[58:61], v[118:121], v[122:125], v[58:61]
	s_waitcnt lgkmcnt(0)
	v_mfma_f32_16x16x32_bf16 v[70:73], v[114:117], v[126:129], v[70:73]
	v_mfma_f32_16x16x32_bf16 v[66:69], v[118:121], v[126:129], v[66:69]
	s_nop 7
	v_cvt_pk_bf16_f32 v106, v42, v43
	v_cvt_pk_bf16_f32 v107, v44, v45
	v_cvt_pk_bf16_f32 v108, v46, v47
	v_cvt_pk_bf16_f32 v109, v48, v49
	ds_write2_b64 v244, v[106:107], v[108:109] offset1:4
	v_add_u32_e32 v110, 0x2000, v244
	v_cvt_pk_bf16_f32 v106, v54, v55
	v_cvt_pk_bf16_f32 v107, v56, v57
	v_cvt_pk_bf16_f32 v108, v50, v51
	v_cvt_pk_bf16_f32 v109, v52, v53
	ds_write2_b64 v110, v[106:107], v[108:109] offset0:32 offset1:36
	v_add_u32_e32 v110, 0x4000, v244
	v_cvt_pk_bf16_f32 v106, v62, v63
	v_cvt_pk_bf16_f32 v107, v64, v65
	v_cvt_pk_bf16_f32 v108, v58, v59
	v_cvt_pk_bf16_f32 v109, v60, v61
	ds_write2_b64 v110, v[106:107], v[108:109] offset0:64 offset1:68
	v_add_u32_e32 v110, 0x6000, v244
	v_cvt_pk_bf16_f32 v106, v70, v71
	v_cvt_pk_bf16_f32 v107, v72, v73
	v_cvt_pk_bf16_f32 v108, v66, v67
	v_cvt_pk_bf16_f32 v109, v68, v69
	ds_write2_b64 v110, v[106:107], v[108:109] offset0:96 offset1:100
	s_cmp_eq_u32 s31, 32
	s_cbranch_scc1 .LBB0_403
